# phase_gates weight staging: 32 loads in flight then counted waits + LDS stores (was 32 serialized round trips)
# speedup vs baseline: 1.0477x; 1.0073x over previous
.LBB0_526:
	s_or_b64 exec, exec, s[0:1]
	s_mov_b64 s[0:1], -1
	s_and_b64 vcc, exec, s[10:11]
	s_waitcnt lgkmcnt(0)
	s_barrier
	s_cbranch_vccz .LBB0_862
	s_add_i32 s0, 0, 0x23fa0
	s_cmp_lg_u32 s0, -1
	s_cselect_b32 s0, s0, 0
	s_cselect_b32 s1, s55, 0
	v_mov_b32_e32 v2, s0
	s_add_i32 s0, 0, 0x23fa4
	s_cmp_lg_u32 s0, -1
	v_mov_b32_e32 v10, v224
	v_mov_b32_e32 v3, s1
	s_cselect_b32 s0, s0, 0
	s_cselect_b32 s1, s55, 0
	flat_load_dword v4, v[2:3] sc0 sc1
	s_waitcnt vmcnt(0)
	v_mov_b32_e32 v2, s0
	v_mov_b32_e32 v3, s1
	flat_load_dword v2, v[2:3] sc0 sc1
	s_waitcnt vmcnt(0)
	v_and_b32_e32 v1, 15, v10
	s_movk_i32 s4, 0x1010
	v_mad_u32_u24 v18, v1, s4, 0
	v_ashrrev_i32_e32 v8, 4, v10
	s_movk_i32 s4, 0x4040
	v_mov_b32_e32 v3, v0
	s_movk_i32 s6, 0x4000
	v_add_u32_e32 v12, 0x200, v10
	v_add_u32_e32 v11, 0x400, v10
	v_add_u32_e32 v13, 0x600, v10
	s_cmp_lg_u32 s57, -1
	s_movk_i32 s7, 0x3000
	s_mov_b32 s8, 0
	s_waitcnt lgkmcnt(0)
	v_readfirstlane_b32 s0, v4
	v_readfirstlane_b32 s1, v2
	s_nop 1
	v_mov_b64_e32 v[4:5], s[0:1]
	v_mad_i64_i32 v[6:7], s[0:1], v8, s4, v[4:5]
	v_lshlrev_b32_e32 v2, 2, v1
	v_lshl_add_u64 v[6:7], v[6:7], 0, v[2:3]
	v_add_co_u32_e32 v6, vcc, s6, v6
	s_nop 1
	v_addc_co_u32_e32 v7, vcc, 0, v7, vcc
	global_load_dword v100, v[6:7], off
	v_lshl_add_u32 v7, v8, 2, v18
	v_mov_b32_e32 v99, v7
	v_ashrrev_i32_e32 v8, 4, v12
	v_mad_i64_i32 v[6:7], s[0:1], v8, s4, v[4:5]
	v_lshl_add_u64 v[6:7], v[6:7], 0, v[2:3]
	v_add_co_u32_e32 v6, vcc, s6, v6
	s_nop 1
	v_addc_co_u32_e32 v7, vcc, 0, v7, vcc
	global_load_dword v101, v[6:7], off
	v_lshl_add_u32 v7, v8, 2, v18
	v_ashrrev_i32_e32 v8, 4, v11
	v_ashrrev_i32_e32 v11, 10, v11
	v_mad_i64_i32 v[6:7], s[0:1], v8, s4, v[4:5]
	v_lshl_add_u64 v[6:7], v[6:7], 0, v[2:3]
	v_add_co_u32_e32 v6, vcc, s6, v6
	s_nop 1
	v_addc_co_u32_e32 v7, vcc, 0, v7, vcc
	global_load_dword v102, v[6:7], off
	v_lshl_add_u32 v7, v8, 2, v18
	v_ashrrev_i32_e32 v8, 4, v13
	v_mad_i64_i32 v[6:7], s[0:1], v8, s4, v[4:5]
	v_lshl_add_u64 v[6:7], v[6:7], 0, v[2:3]
	v_add_co_u32_e32 v6, vcc, s6, v6
	s_nop 1
	v_addc_co_u32_e32 v7, vcc, 0, v7, vcc
	global_load_dword v103, v[6:7], off
	v_lshl_add_u32 v7, v8, 2, v18
	v_add_u32_e32 v6, 0x800, v10
	v_ashrrev_i32_e32 v7, 4, v6
	v_mad_i64_i32 v[8:9], s[0:1], v7, s4, v[4:5]
	v_lshl_add_u64 v[8:9], v[8:9], 0, v[2:3]
	v_add_co_u32_e32 v8, vcc, s6, v8
	v_lshl_add_u32 v7, v7, 2, v18
	s_nop 0
	v_addc_co_u32_e32 v9, vcc, 0, v9, vcc
	global_load_dword v104, v[8:9], off
	v_ashrrev_i32_e32 v6, 10, v6
	v_add_u32_e32 v8, 0xa00, v10
	v_ashrrev_i32_e32 v7, 4, v8
	v_mad_i64_i32 v[14:15], s[0:1], v7, s4, v[4:5]
	v_lshl_add_u64 v[14:15], v[14:15], 0, v[2:3]
	v_add_co_u32_e32 v14, vcc, s6, v14
	v_lshl_add_u32 v7, v7, 2, v18
	s_nop 0
	v_addc_co_u32_e32 v15, vcc, 0, v15, vcc
	global_load_dword v105, v[14:15], off
	v_add_u32_e32 v7, 0xc00, v10
	v_ashrrev_i32_e32 v9, 4, v7
	v_mad_i64_i32 v[14:15], s[0:1], v9, s4, v[4:5]
	v_lshl_add_u64 v[14:15], v[14:15], 0, v[2:3]
	v_add_co_u32_e32 v14, vcc, s6, v14
	v_lshl_add_u32 v9, v9, 2, v18
	s_nop 0
	v_addc_co_u32_e32 v15, vcc, 0, v15, vcc
	global_load_dword v106, v[14:15], off
	v_add_u32_e32 v9, 0xe00, v10
	v_ashrrev_i32_e32 v16, 4, v9
	v_mad_i64_i32 v[14:15], s[0:1], v16, s4, v[4:5]
	v_lshl_add_u64 v[14:15], v[14:15], 0, v[2:3]
	v_add_co_u32_e32 v14, vcc, s6, v14
	s_nop 1
	v_addc_co_u32_e32 v15, vcc, 0, v15, vcc
	global_load_dword v107, v[14:15], off
	v_lshl_add_u32 v15, v16, 2, v18
	v_add_u32_e32 v15, 0x1000, v10
	v_ashrrev_i32_e32 v14, 4, v15
	v_mad_i64_i32 v[16:17], s[0:1], v14, s4, v[4:5]
	v_lshl_add_u64 v[16:17], v[16:17], 0, v[2:3]
	v_add_co_u32_e32 v16, vcc, s6, v16
	v_lshl_add_u32 v14, v14, 2, v18
	s_nop 0
	v_addc_co_u32_e32 v17, vcc, 0, v17, vcc
	global_load_dword v108, v[16:17], off
	v_add_u32_e32 v14, 0x1200, v10
	v_ashrrev_i32_e32 v19, 4, v14
	v_mad_i64_i32 v[16:17], s[0:1], v19, s4, v[4:5]
	v_lshl_add_u64 v[16:17], v[16:17], 0, v[2:3]
	v_add_co_u32_e32 v16, vcc, s6, v16
	s_nop 1
	v_addc_co_u32_e32 v17, vcc, 0, v17, vcc
	global_load_dword v109, v[16:17], off
	v_lshl_add_u32 v17, v19, 2, v18
	v_add_u32_e32 v16, 0x1400, v10
	v_ashrrev_i32_e32 v19, 4, v16
	v_mad_i64_i32 v[16:17], s[0:1], v19, s4, v[4:5]
	v_lshl_add_u64 v[16:17], v[16:17], 0, v[2:3]
	v_add_co_u32_e32 v16, vcc, s6, v16
	s_nop 1
	v_addc_co_u32_e32 v17, vcc, 0, v17, vcc
	global_load_dword v110, v[16:17], off
	v_lshl_add_u32 v17, v19, 2, v18
	v_add_u32_e32 v16, 0x1600, v10
	v_ashrrev_i32_e32 v19, 4, v16
	v_mad_i64_i32 v[16:17], s[0:1], v19, s4, v[4:5]
	v_lshl_add_u64 v[16:17], v[16:17], 0, v[2:3]
	v_add_co_u32_e32 v16, vcc, s6, v16
	s_nop 1
	v_addc_co_u32_e32 v17, vcc, 0, v17, vcc
	global_load_dword v111, v[16:17], off
	v_lshl_add_u32 v17, v19, 2, v18
	v_add_u32_e32 v16, 0x1800, v10
	v_ashrrev_i32_e32 v19, 4, v16
	v_mad_i64_i32 v[16:17], s[0:1], v19, s4, v[4:5]
	v_lshl_add_u64 v[16:17], v[16:17], 0, v[2:3]
	v_add_co_u32_e32 v16, vcc, s6, v16
	s_nop 1
	v_addc_co_u32_e32 v17, vcc, 0, v17, vcc
	global_load_dword v112, v[16:17], off
	v_lshl_add_u32 v17, v19, 2, v18
	v_add_u32_e32 v16, 0x1a00, v10
	v_ashrrev_i32_e32 v19, 4, v16
	v_mad_i64_i32 v[16:17], s[0:1], v19, s4, v[4:5]
	v_lshl_add_u64 v[16:17], v[16:17], 0, v[2:3]
	v_add_co_u32_e32 v16, vcc, s6, v16
	s_nop 1
	v_addc_co_u32_e32 v17, vcc, 0, v17, vcc
	global_load_dword v113, v[16:17], off
	v_lshl_add_u32 v17, v19, 2, v18
	v_add_u32_e32 v16, 0x1c00, v10
	v_ashrrev_i32_e32 v19, 4, v16
	v_mad_i64_i32 v[16:17], s[0:1], v19, s4, v[4:5]
	v_lshl_add_u64 v[16:17], v[16:17], 0, v[2:3]
	v_add_co_u32_e32 v16, vcc, s6, v16
	s_nop 1
	v_addc_co_u32_e32 v17, vcc, 0, v17, vcc
	global_load_dword v114, v[16:17], off
	v_lshl_add_u32 v17, v19, 2, v18
	v_add_u32_e32 v16, 0x1e00, v10
	v_ashrrev_i32_e32 v19, 4, v16
	v_mad_i64_i32 v[16:17], s[0:1], v19, s4, v[4:5]
	v_lshl_add_u64 v[16:17], v[16:17], 0, v[2:3]
	v_add_co_u32_e32 v16, vcc, s6, v16
	s_nop 1
	v_addc_co_u32_e32 v17, vcc, 0, v17, vcc
	global_load_dword v115, v[16:17], off
	v_lshl_add_u32 v17, v19, 2, v18
	v_add_u32_e32 v16, 0x2000, v10
	v_ashrrev_i32_e32 v19, 4, v16
	v_mad_i64_i32 v[16:17], s[0:1], v19, s4, v[4:5]
	v_lshl_add_u64 v[16:17], v[16:17], 0, v[2:3]
	v_add_co_u32_e32 v16, vcc, s6, v16
	s_nop 1
	v_addc_co_u32_e32 v17, vcc, 0, v17, vcc
	global_load_dword v116, v[16:17], off
	v_lshl_add_u32 v17, v19, 2, v18
	v_add_u32_e32 v16, 0x2200, v10
	v_ashrrev_i32_e32 v19, 4, v16
	v_mad_i64_i32 v[16:17], s[0:1], v19, s4, v[4:5]
	v_lshl_add_u64 v[16:17], v[16:17], 0, v[2:3]
	v_add_co_u32_e32 v16, vcc, s6, v16
	s_nop 1
	v_addc_co_u32_e32 v17, vcc, 0, v17, vcc
	global_load_dword v117, v[16:17], off
	v_lshl_add_u32 v17, v19, 2, v18
	v_add_u32_e32 v16, 0x2400, v10
	v_ashrrev_i32_e32 v19, 4, v16
	v_mad_i64_i32 v[16:17], s[0:1], v19, s4, v[4:5]
	v_lshl_add_u64 v[16:17], v[16:17], 0, v[2:3]
	v_add_co_u32_e32 v16, vcc, s6, v16
	s_nop 1
	v_addc_co_u32_e32 v17, vcc, 0, v17, vcc
	global_load_dword v118, v[16:17], off
	v_lshl_add_u32 v17, v19, 2, v18
	v_add_u32_e32 v16, 0x2600, v10
	v_ashrrev_i32_e32 v19, 4, v16
	v_mad_i64_i32 v[16:17], s[0:1], v19, s4, v[4:5]
	v_lshl_add_u64 v[16:17], v[16:17], 0, v[2:3]
	v_add_co_u32_e32 v16, vcc, s6, v16
	s_nop 1
	v_addc_co_u32_e32 v17, vcc, 0, v17, vcc
	global_load_dword v119, v[16:17], off
	v_lshl_add_u32 v17, v19, 2, v18
	v_add_u32_e32 v16, 0x2800, v10
	v_ashrrev_i32_e32 v19, 4, v16
	v_mad_i64_i32 v[16:17], s[0:1], v19, s4, v[4:5]
	v_lshl_add_u64 v[16:17], v[16:17], 0, v[2:3]
	v_add_co_u32_e32 v16, vcc, s6, v16
	s_nop 1
	v_addc_co_u32_e32 v17, vcc, 0, v17, vcc
	global_load_dword v120, v[16:17], off
	v_lshl_add_u32 v17, v19, 2, v18
	v_add_u32_e32 v16, 0x2a00, v10
	v_ashrrev_i32_e32 v19, 4, v16
	v_mad_i64_i32 v[16:17], s[0:1], v19, s4, v[4:5]
	v_lshl_add_u64 v[16:17], v[16:17], 0, v[2:3]
	v_add_co_u32_e32 v16, vcc, s6, v16
	s_nop 1
	v_addc_co_u32_e32 v17, vcc, 0, v17, vcc
	global_load_dword v121, v[16:17], off
	v_lshl_add_u32 v17, v19, 2, v18
	v_add_u32_e32 v16, 0x2c00, v10
	v_ashrrev_i32_e32 v19, 4, v16
	v_mad_i64_i32 v[16:17], s[0:1], v19, s4, v[4:5]
	v_lshl_add_u64 v[16:17], v[16:17], 0, v[2:3]
	v_add_co_u32_e32 v16, vcc, s6, v16
	s_nop 1
	v_addc_co_u32_e32 v17, vcc, 0, v17, vcc
	global_load_dword v122, v[16:17], off
	v_lshl_add_u32 v17, v19, 2, v18
	v_add_u32_e32 v16, 0x2e00, v10
	v_ashrrev_i32_e32 v19, 4, v16
	v_mad_i64_i32 v[16:17], s[0:1], v19, s4, v[4:5]
	v_lshl_add_u64 v[16:17], v[16:17], 0, v[2:3]
	v_add_co_u32_e32 v16, vcc, s6, v16
	s_nop 1
	v_addc_co_u32_e32 v17, vcc, 0, v17, vcc
	global_load_dword v123, v[16:17], off
	v_lshl_add_u32 v17, v19, 2, v18
	v_add_u32_e32 v16, 0x3000, v10
	v_ashrrev_i32_e32 v19, 4, v16
	v_mad_i64_i32 v[16:17], s[0:1], v19, s4, v[4:5]
	v_lshl_add_u64 v[16:17], v[16:17], 0, v[2:3]
	v_add_co_u32_e32 v16, vcc, s6, v16
	s_nop 1
	v_addc_co_u32_e32 v17, vcc, 0, v17, vcc
	global_load_dword v124, v[16:17], off
	v_lshl_add_u32 v17, v19, 2, v18
	v_add_u32_e32 v16, 0x3200, v10
	v_ashrrev_i32_e32 v19, 4, v16
	v_mad_i64_i32 v[16:17], s[0:1], v19, s4, v[4:5]
	v_lshl_add_u64 v[16:17], v[16:17], 0, v[2:3]
	v_add_co_u32_e32 v16, vcc, s6, v16
	s_nop 1
	v_addc_co_u32_e32 v17, vcc, 0, v17, vcc
	global_load_dword v125, v[16:17], off
	v_lshl_add_u32 v17, v19, 2, v18
	v_add_u32_e32 v16, 0x3400, v10
	v_ashrrev_i32_e32 v19, 4, v16
	v_mad_i64_i32 v[16:17], s[0:1], v19, s4, v[4:5]
	v_lshl_add_u64 v[16:17], v[16:17], 0, v[2:3]
	v_add_co_u32_e32 v16, vcc, s6, v16
	s_nop 1
	v_addc_co_u32_e32 v17, vcc, 0, v17, vcc
	global_load_dword v126, v[16:17], off
	v_lshl_add_u32 v17, v19, 2, v18
	v_add_u32_e32 v16, 0x3600, v10
	v_ashrrev_i32_e32 v19, 4, v16
	v_mad_i64_i32 v[16:17], s[0:1], v19, s4, v[4:5]
	v_lshl_add_u64 v[16:17], v[16:17], 0, v[2:3]
	v_add_co_u32_e32 v16, vcc, s6, v16
	s_nop 1
	v_addc_co_u32_e32 v17, vcc, 0, v17, vcc
	global_load_dword v127, v[16:17], off
	v_lshl_add_u32 v17, v19, 2, v18
	v_add_u32_e32 v16, 0x3800, v10
	v_ashrrev_i32_e32 v19, 4, v16
	v_mad_i64_i32 v[16:17], s[0:1], v19, s4, v[4:5]
	v_lshl_add_u64 v[16:17], v[16:17], 0, v[2:3]
	v_add_co_u32_e32 v16, vcc, s6, v16
	s_nop 1
	v_addc_co_u32_e32 v17, vcc, 0, v17, vcc
	global_load_dword v128, v[16:17], off
	v_lshl_add_u32 v17, v19, 2, v18
	v_add_u32_e32 v16, 0x3a00, v10
	v_ashrrev_i32_e32 v19, 4, v16
	v_mad_i64_i32 v[16:17], s[0:1], v19, s4, v[4:5]
	v_lshl_add_u64 v[16:17], v[16:17], 0, v[2:3]
	v_add_co_u32_e32 v16, vcc, s6, v16
	s_nop 1
	v_addc_co_u32_e32 v17, vcc, 0, v17, vcc
	global_load_dword v129, v[16:17], off
	v_lshl_add_u32 v17, v19, 2, v18
	v_add_u32_e32 v16, 0x3c00, v10
	v_ashrrev_i32_e32 v19, 4, v16
	v_mad_i64_i32 v[16:17], s[0:1], v19, s4, v[4:5]
	v_lshl_add_u64 v[16:17], v[16:17], 0, v[2:3]
	v_add_co_u32_e32 v16, vcc, s6, v16
	s_nop 1
	v_addc_co_u32_e32 v17, vcc, 0, v17, vcc
	global_load_dword v130, v[16:17], off
	v_lshl_add_u32 v17, v19, 2, v18
	v_add_u32_e32 v16, 0x3e00, v10
	v_ashrrev_i32_e32 v16, 4, v16
	v_mad_i64_i32 v[4:5], s[0:1], v16, s4, v[4:5]
	v_lshl_add_u64 v[4:5], v[4:5], 0, v[2:3]
	v_add_co_u32_e32 v4, vcc, s6, v4
	s_cselect_b32 s0, s57, 0
	s_nop 0
	v_addc_co_u32_e32 v5, vcc, 0, v5, vcc
	global_load_dword v131, v[4:5], off
	v_lshl_add_u32 v4, v16, 2, v18
	s_cselect_b32 s1, s55, 0
	s_cmp_lg_u32 s58, -1
	v_mov_b32_e32 v5, s1
	s_cselect_b32 s1, s55, 0
	s_waitcnt vmcnt(31)
	ds_write_b32 v99, v100
	s_waitcnt vmcnt(30)
	ds_write_b32 v99, v101 offset:128
	s_waitcnt vmcnt(29)
	ds_write_b32 v99, v102 offset:256
	s_waitcnt vmcnt(28)
	ds_write_b32 v99, v103 offset:384
	s_waitcnt vmcnt(27)
	ds_write_b32 v99, v104 offset:512
	s_waitcnt vmcnt(26)
	ds_write_b32 v99, v105 offset:640
	s_waitcnt vmcnt(25)
	ds_write_b32 v99, v106 offset:768
	s_waitcnt vmcnt(24)
	ds_write_b32 v99, v107 offset:896
	s_waitcnt vmcnt(23)
	ds_write_b32 v99, v108 offset:1024
	s_waitcnt vmcnt(22)
	ds_write_b32 v99, v109 offset:1152
	s_waitcnt vmcnt(21)
	ds_write_b32 v99, v110 offset:1280
	s_waitcnt vmcnt(20)
	ds_write_b32 v99, v111 offset:1408
	s_waitcnt vmcnt(19)
	ds_write_b32 v99, v112 offset:1536
	s_waitcnt vmcnt(18)
	ds_write_b32 v99, v113 offset:1664
	s_waitcnt vmcnt(17)
	ds_write_b32 v99, v114 offset:1792
	s_waitcnt vmcnt(16)
	ds_write_b32 v99, v115 offset:1920
	s_waitcnt vmcnt(15)
	ds_write_b32 v99, v116 offset:2048
	s_waitcnt vmcnt(14)
	ds_write_b32 v99, v117 offset:2176
	s_waitcnt vmcnt(13)
	ds_write_b32 v99, v118 offset:2304
	s_waitcnt vmcnt(12)
	ds_write_b32 v99, v119 offset:2432
	s_waitcnt vmcnt(11)
	ds_write_b32 v99, v120 offset:2560
	s_waitcnt vmcnt(10)
	ds_write_b32 v99, v121 offset:2688
	s_waitcnt vmcnt(9)
	ds_write_b32 v99, v122 offset:2816
	s_waitcnt vmcnt(8)
	ds_write_b32 v99, v123 offset:2944
	s_waitcnt vmcnt(7)
	ds_write_b32 v99, v124 offset:3072
	s_waitcnt vmcnt(6)
	ds_write_b32 v99, v125 offset:3200
	s_waitcnt vmcnt(5)
	ds_write_b32 v99, v126 offset:3328
	s_waitcnt vmcnt(4)
	ds_write_b32 v99, v127 offset:3456
	s_waitcnt vmcnt(3)
	ds_write_b32 v99, v128 offset:3584
	s_waitcnt vmcnt(2)
	ds_write_b32 v99, v129 offset:3712
	s_waitcnt vmcnt(1)
	ds_write_b32 v99, v130 offset:3840
	s_waitcnt vmcnt(0)
	ds_write_b32 v99, v131 offset:3968
	v_mov_b32_e32 v4, s0
	s_cselect_b32 s0, s58, 0
	flat_load_dword v3, v[4:5] sc0 sc1
	s_waitcnt vmcnt(0)
	v_mov_b32_e32 v4, s0
	v_mov_b32_e32 v5, s1
	flat_load_dword v4, v[4:5] sc0 sc1
	s_waitcnt vmcnt(0) lgkmcnt(0)
	v_readfirstlane_b32 s0, v3
	s_add_u32 s0, s0, 0x2d000
	v_readfirstlane_b32 s1, v4
	s_addc_u32 s1, s1, 0
	s_cmp_lg_u32 s50, -1
	s_cselect_b32 s4, s50, 0
	s_cselect_b32 s5, s55, 0
	s_cmp_lg_u32 s51, -1
	v_mov_b32_e32 v4, s4
	v_mov_b32_e32 v5, s5
	s_cselect_b32 s4, s51, 0
	s_cselect_b32 s5, s55, 0
	flat_load_dword v3, v[4:5] sc0 sc1
	s_waitcnt vmcnt(0)
	v_mov_b32_e32 v4, s4
	v_mov_b32_e32 v5, s5
	flat_load_dword v4, v[4:5] sc0 sc1
	s_waitcnt vmcnt(0)
	v_mov_b32_e32 v5, v0
	s_waitcnt lgkmcnt(0)
	v_readfirstlane_b32 s4, v3
	v_ashrrev_i32_e32 v3, 10, v10
	v_mul_hi_i32_i24_e32 v17, 0x9000, v3
	v_readfirstlane_b32 s5, v4
	v_and_b32_e32 v4, 0x3ff, v10
	v_mul_i32_i24_e32 v16, 0x9000, v3
	v_lshlrev_b32_e32 v4, 2, v4
	v_lshl_add_u64 v[16:17], s[0:1], 0, v[16:17]
	v_lshl_add_u64 v[16:17], v[16:17], 0, v[4:5]
	v_add_co_u32_e32 v20, vcc, s6, v16
	s_add_u32 s4, s4, 0x1000
	s_nop 0
	v_addc_co_u32_e32 v21, vcc, 0, v17, vcc
	v_add_co_u32_e32 v16, vcc, s7, v16
	global_load_dword v3, v[20:21], off
	s_nop 0
	v_addc_co_u32_e32 v17, vcc, 0, v17, vcc
	global_load_dword v24, v[16:17], off
	v_ashrrev_i32_e32 v20, 10, v12
	v_and_b32_e32 v12, 0x3ff, v12
	v_mul_hi_i32_i24_e32 v21, 0x9000, v20
	v_mul_i32_i24_e32 v20, 0x9000, v20
	s_addc_u32 s5, s5, 0
	v_lshlrev_b32_e32 v16, 2, v12
	v_mov_b32_e32 v17, v0
	v_lshl_add_u64 v[20:21], s[0:1], 0, v[20:21]
	global_load_dword v19, v4, s[4:5]
	global_load_dword v12, v16, s[4:5]
	v_lshl_add_u64 v[16:17], v[20:21], 0, v[16:17]
	v_add_co_u32_e32 v20, vcc, s6, v16
	s_waitcnt vmcnt(3)
	v_add_f32_e32 v3, 1.0, v3
	v_addc_co_u32_e32 v21, vcc, 0, v17, vcc
	global_load_dword v20, v[20:21], off
	v_add_co_u32_e32 v16, vcc, s7, v16
	s_waitcnt vmcnt(2)
	v_mul_f32_e32 v22, v19, v3
	v_lshl_add_u32 v3, v10, 2, 0
	v_add_u32_e32 v23, 0x10200, v3
	v_addc_co_u32_e32 v17, vcc, 0, v17, vcc
	v_add_u32_e32 v3, 0x15200, v3
	s_waitcnt vmcnt(0)
	v_add_f32_e32 v20, 1.0, v20
	v_mul_f32_e32 v12, v12, v20
	ds_write2st64_b32 v23, v22, v12 offset1:8
	global_load_dword v12, v[16:17], off
	v_mul_hi_i32_i24_e32 v17, 0x9000, v11
	v_mul_i32_i24_e32 v16, 0x9000, v11
	v_lshl_add_u64 v[16:17], s[0:1], 0, v[16:17]
	v_lshl_add_u64 v[16:17], v[16:17], 0, v[4:5]
	v_add_co_u32_e32 v20, vcc, s6, v16
	s_waitcnt vmcnt(0)
	ds_write2st64_b32 v3, v24, v12 offset1:8
	v_addc_co_u32_e32 v21, vcc, 0, v17, vcc
	v_add_co_u32_e32 v16, vcc, s7, v16
	global_load_dword v11, v[20:21], off
	s_nop 0
	v_addc_co_u32_e32 v17, vcc, 0, v17, vcc
	global_load_dword v20, v[16:17], off
	v_ashrrev_i32_e32 v16, 10, v13
	v_and_b32_e32 v12, 0x3ff, v13
	v_mul_hi_i32_i24_e32 v17, 0x9000, v16
	v_mul_i32_i24_e32 v16, 0x9000, v16
	v_lshlrev_b32_e32 v12, 2, v12
	v_mov_b32_e32 v13, v0
	v_lshl_add_u64 v[16:17], s[0:1], 0, v[16:17]
	global_load_dword v21, v12, s[4:5]
	v_lshl_add_u64 v[12:13], v[16:17], 0, v[12:13]
	v_add_co_u32_e32 v16, vcc, s6, v12
	s_waitcnt vmcnt(2)
	v_add_f32_e32 v11, 1.0, v11
	v_addc_co_u32_e32 v17, vcc, 0, v13, vcc
	global_load_dword v16, v[16:17], off
	v_add_co_u32_e32 v12, vcc, s7, v12
	v_mul_f32_e32 v11, v19, v11
	s_nop 0
	v_addc_co_u32_e32 v13, vcc, 0, v13, vcc
	s_waitcnt vmcnt(0)
	v_add_f32_e32 v16, 1.0, v16
	v_mul_f32_e32 v16, v21, v16
	ds_write2st64_b32 v23, v11, v16 offset0:16 offset1:24
	global_load_dword v11, v[12:13], off
	v_mul_hi_i32_i24_e32 v13, 0x9000, v6
	v_mul_i32_i24_e32 v12, 0x9000, v6
	v_lshl_add_u64 v[12:13], s[0:1], 0, v[12:13]
	v_lshl_add_u64 v[12:13], v[12:13], 0, v[4:5]
	v_add_co_u32_e32 v16, vcc, s6, v12
	s_waitcnt vmcnt(0)
	ds_write2st64_b32 v3, v20, v11 offset0:16 offset1:24
	v_addc_co_u32_e32 v17, vcc, 0, v13, vcc
	v_add_co_u32_e32 v12, vcc, s7, v12
	global_load_dword v6, v[16:17], off
	s_nop 0
	v_addc_co_u32_e32 v13, vcc, 0, v13, vcc
	global_load_dword v11, v[12:13], off
	v_ashrrev_i32_e32 v16, 10, v8
	v_and_b32_e32 v8, 0x3ff, v8
	v_mul_hi_i32_i24_e32 v17, 0x9000, v16
	v_mul_i32_i24_e32 v16, 0x9000, v16
	v_lshlrev_b32_e32 v12, 2, v8
	v_mov_b32_e32 v13, v0
	v_lshl_add_u64 v[16:17], s[0:1], 0, v[16:17]
	global_load_dword v8, v12, s[4:5]
	v_lshl_add_u64 v[12:13], v[16:17], 0, v[12:13]
	v_add_co_u32_e32 v16, vcc, s6, v12
	s_waitcnt vmcnt(2)
	v_add_f32_e32 v6, 1.0, v6
	v_addc_co_u32_e32 v17, vcc, 0, v13, vcc
	global_load_dword v16, v[16:17], off
	v_add_co_u32_e32 v12, vcc, s7, v12
	v_mul_f32_e32 v6, v19, v6
	s_nop 0
	v_addc_co_u32_e32 v13, vcc, 0, v13, vcc
	s_waitcnt vmcnt(0)
	v_add_f32_e32 v16, 1.0, v16
	v_mul_f32_e32 v8, v8, v16
	ds_write2st64_b32 v23, v6, v8 offset0:32 offset1:40
	global_load_dword v6, v[12:13], off
	s_waitcnt vmcnt(0)
	ds_write2st64_b32 v3, v11, v6 offset0:32 offset1:40
	v_ashrrev_i32_e32 v6, 10, v7
	v_mul_hi_i32_i24_e32 v7, 0x9000, v6
	v_mul_i32_i24_e32 v6, 0x9000, v6
	v_lshl_add_u64 v[6:7], s[0:1], 0, v[6:7]
	v_lshl_add_u64 v[6:7], v[6:7], 0, v[4:5]
	v_add_co_u32_e32 v12, vcc, s6, v6
	s_nop 1
	v_addc_co_u32_e32 v13, vcc, 0, v7, vcc
	global_load_dword v8, v[12:13], off
	v_add_co_u32_e32 v6, vcc, s7, v6
	s_waitcnt vmcnt(0)
	v_add_f32_e32 v8, 1.0, v8
	v_mul_f32_e32 v11, v19, v8
	v_addc_co_u32_e32 v7, vcc, 0, v7, vcc
	v_ashrrev_i32_e32 v8, 10, v9
	global_load_dword v12, v[6:7], off
	v_and_b32_e32 v6, 0x3ff, v9
	v_mul_hi_i32_i24_e32 v9, 0x9000, v8
	v_mul_i32_i24_e32 v8, 0x9000, v8
	v_lshlrev_b32_e32 v6, 2, v6
	v_mov_b32_e32 v7, v0
	v_lshl_add_u64 v[8:9], s[0:1], 0, v[8:9]
	global_load_dword v13, v6, s[4:5]
	v_lshl_add_u64 v[6:7], v[8:9], 0, v[6:7]
	v_add_co_u32_e32 v8, vcc, s6, v6
	s_nop 1
	v_addc_co_u32_e32 v9, vcc, 0, v7, vcc
	v_add_co_u32_e32 v6, vcc, s7, v6
	global_load_dword v8, v[8:9], off
	s_nop 0
	v_addc_co_u32_e32 v7, vcc, 0, v7, vcc
	global_load_dword v6, v[6:7], off
	s_waitcnt vmcnt(1)
	v_add_f32_e32 v8, 1.0, v8
	v_mul_f32_e32 v8, v13, v8
	ds_write2st64_b32 v23, v11, v8 offset0:48 offset1:56
	s_waitcnt vmcnt(0)
	ds_write2st64_b32 v3, v12, v6 offset0:48 offset1:56
	v_ashrrev_i32_e32 v6, 10, v15
	v_mul_hi_i32_i24_e32 v7, 0x9000, v6
	v_mul_i32_i24_e32 v6, 0x9000, v6
	v_lshl_add_u64 v[6:7], s[0:1], 0, v[6:7]
	v_lshl_add_u64 v[4:5], v[6:7], 0, v[4:5]
	v_add_co_u32_e32 v6, vcc, s6, v4
	s_nop 1
	v_addc_co_u32_e32 v7, vcc, 0, v5, vcc
	global_load_dword v6, v[6:7], off
	v_add_co_u32_e32 v4, vcc, s7, v4
	s_nop 1
	v_addc_co_u32_e32 v5, vcc, 0, v5, vcc
	global_load_dword v9, v[4:5], off
	v_and_b32_e32 v4, 0x3ff, v14
	v_lshlrev_b32_e32 v4, 2, v4
	v_mov_b32_e32 v5, v0
	global_load_dword v11, v4, s[4:5]
	s_waitcnt vmcnt(2)
	v_add_f32_e32 v6, 1.0, v6
	v_mul_f32_e32 v8, v19, v6
	v_ashrrev_i32_e32 v6, 10, v14
	v_mul_hi_i32_i24_e32 v7, 0x9000, v6
	v_mul_i32_i24_e32 v6, 0x9000, v6
	v_lshl_add_u64 v[6:7], s[0:1], 0, v[6:7]
	v_lshl_add_u64 v[4:5], v[6:7], 0, v[4:5]
	v_add_co_u32_e32 v6, vcc, s6, v4
	v_readlane_b32 s0, v253, 18
	s_nop 0
	v_addc_co_u32_e32 v7, vcc, 0, v5, vcc
	global_load_dword v6, v[6:7], off
	v_add_co_u32_e32 v4, vcc, 0x3000, v4
	v_readlane_b32 s1, v253, 19
	s_nop 0
	v_addc_co_u32_e32 v5, vcc, 0, v5, vcc
	global_load_dword v4, v[4:5], off
	s_andn2_b64 vcc, exec, s[0:1]
	s_waitcnt vmcnt(1)
	v_add_f32_e32 v6, 1.0, v6
	v_mul_f32_e32 v6, v11, v6
	ds_write2st64_b32 v23, v8, v6 offset0:64 offset1:72
	s_waitcnt vmcnt(0)
	ds_write2st64_b32 v3, v9, v4 offset0:64 offset1:72
	s_waitcnt lgkmcnt(0)
	s_barrier
	s_cbranch_vccnz .LBB0_529
	v_readlane_b32 s8, v253, 56
